# thin phase staggered: workgroups 64..127 run their short-conv items (items 0..3327, stride 512) before the attention unit; workgroups 128..255 keep 1 item per wave at the end
# baseline (speedup 1.0000x reference)
; #define LAS __attribute__((address_space(3)))
; __global__ void __launch_bounds__(512, 2) mk_fwd(Args args) {
;     extern __shared__ __attribute__((aligned(16))) unsigned char lds_raw[];
;     LAS unsigned char* lds = (LAS unsigned char*)lds_raw;
;     volatile LAS unsigned* MISC = (volatile LAS unsigned*)(lds + MISC_OFF);
;     const int tid = threadIdx.x, lane = tid & 63, wave = __builtin_amdgcn_readfirstlane(tid >> 6);
;     const int G = gridDim.x, bx = blockIdx.x;
;     const int vcu = (G % 8 == 0) ? (bx % 8) * (G / 8) + bx / 8 : bx;
;     const int gw = vcu * 8 + wave, ngw = G * 8;
_Z6mk_fwd4Args:
	s_mov_b32 s98, 0
	v_writelane_b32 v255, s98, 43
	s_load_dword s85, s[0:1], 0x108
	s_mov_b64 s[88:89], s[0:1]
	s_add_u32 s0, s88, 0x108
	s_addc_u32 s1, s89, 0
	s_mov_b32 s97, s2
	v_writelane_b32 v249, s0, 0
	v_readfirstlane_b32 s82, v0
	s_nop 0
	v_writelane_b32 v249, s1, 1
	s_waitcnt lgkmcnt(0)
	s_and_b32 s0, s85, 7
	s_cmp_lg_u32 s0, 0
	v_writelane_b32 v249, s97, 2
	s_cbranch_scc1 .LBB0_2
	s_ashr_i32 s1, s97, 31
	s_lshr_b32 s1, s1, 29
	s_add_i32 s1, s97, s1
	s_ashr_i32 s2, s1, 3
	s_and_b32 s1, s1, -8
	s_ashr_i32 s0, s85, 3
	s_sub_i32 s1, s97, s1
	s_mul_i32 s0, s0, s1
	s_add_i32 s0, s0, s2
	v_writelane_b32 v249, s0, 2

; __device__ __forceinline__ void sconv_item(const Args& args, int l, int item, int lane) {
;     asm volatile("" : "+v"(lane));
;     unsigned char* ws = args.ws;
;     const bf16_t* PROJ = (const bf16_t*)(ws + WS_PROJ); bf16_t* ACONV = (bf16_t*)(ws + WS_ABR + SZ_ABR1);
;     const int tb = item >> 1, c0 = (item & 1) * 512 + lane * 8, row0 = tb * 8;
;     const bool smp = row0 >= MP;
;     const int b = smp ? (row0 - MP) / DSEQ : row0 / SEQ, t0 = smp ? (row0 - MP) % DSEQ : row0 % SEQ, T = smp ? DSEQ : SEQ;
;     const float* cw = args.in[I_SCW] + (size_t)l * 3 * LW + c0;
; __global__ void __launch_bounds__(512, 2) mk_fwd(Args args) {
;     ...
;             if (G == 256) {
;                 if (vcu >= 128) attn_sample_unit(args, l, vcu - 128, lds, tid);
;     ...
;                 if (vcu >= 64) for (int it = (vcu - 64) * 8 + wave; it < (MT / 8) * 2; it += 192 * 8) sconv_item(args, l, it, lane);
.LBB0_644:
	v_readlane_b32 s0, v255, 43
	s_nop 1
	s_cmp_lg_u32 s0, 0
	s_cbranch_scc1 .Lsc_ret
	v_readlane_b32 s1, v249, 2
	s_nop 1
	s_sub_i32 s1, s1, 64
	s_cmp_lt_u32 s1, 64
	s_cbranch_scc0 .Lsc_go_on
	s_mov_b32 s0, 1
	v_writelane_b32 v255, s0, 43
	v_readlane_b32 s4, v255, 39
	v_readlane_b32 s2, v255, 18
	v_readlane_b32 s5, v255, 40
	v_readlane_b32 s3, v255, 19
	s_mul_i32 s1, s4, 0x3000
	s_mul_hi_u32 s0, s4, 0x3000
	s_add_u32 s30, s2, s1
	s_addc_u32 s31, s3, s0
	s_lshl_b64 s[0:1], s[4:5], 18
	v_readlane_b32 s52, v252, 7
	v_readlane_b32 s53, v252, 8
	s_nop 1
	s_add_u32 s26, s52, s0
	s_addc_u32 s27, s53, s1
	s_branch .LBB0_658
.Lsc_ret:
	s_mov_b32 s0, 2
	v_writelane_b32 v255, s0, 43

; __global__ void __launch_bounds__(512, 2) mk_fwd(Args args) {
;     ...
;             if (G == 256) {
;                 if (vcu >= 128) attn_sample_unit(args, l, vcu - 128, lds, tid);
;     ...
;                 if (vcu >= 64) for (int it = (vcu - 64) * 8 + wave; it < (MT / 8) * 2; it += 192 * 8) sconv_item(args, l, it, lane);
;     ...
;             } else {
;                 for (int u = vcu; u < 128; u += G) attn_sample_unit(args, l, u, lds, tid);
;     ...
;                 for (int it = gw; it < (MT / 8) * 2; it += ngw) sconv_item(args, l, it, lane);
.LBB0_658:
	v_readlane_b32 s0, v255, 43
	s_nop 1
	s_cmp_eq_u32 s0, 2
	s_cbranch_scc1 .LBB0_659
	v_readlane_b32 s0, v253, 52
	v_readlane_b32 s1, v253, 53
	s_andn2_b64 vcc, exec, s[0:1]
	v_readlane_b32 s2, v254, 49
	v_readlane_b32 s3, v254, 42
	v_readlane_b32 s14, v254, 47
	v_readlane_b32 s4, v249, 2
	s_movk_i32 s5, 0x200
	s_movk_i32 s6, 0x6ff
	s_cmp_lt_u32 s4, 0x80
	s_cbranch_scc1 .Lsc_setA
	s_add_i32 s14, s14, 0xb00
	s_add_i32 s2, s2, 0x2c00
	s_add_i32 s3, s3, 0x160000
	s_movk_i32 s5, 0x400
	s_movk_i32 s6, 0xaff
.Lsc_setA:
	v_writelane_b32 v255, s5, 44
	v_writelane_b32 v255, s6, 45
	s_cbranch_vccz .LBB0_686
.LBB0_659:
	v_readlane_b32 s0, v255, 43
	s_nop 1
	s_cmp_eq_u32 s0, 1
	s_cbranch_scc1 .LBB0_644
	s_mov_b32 s0, 0
	v_writelane_b32 v255, s0, 43
	v_readlane_b32 s0, v255, 41
	s_add_i32 s2, s0, 4
	s_cmp_ge_i32 s2, s47
	s_cbranch_scc1 .LBB0_752
	s_waitcnt vmcnt(0)
	s_waitcnt vmcnt(0)
	s_barrier
	s_mov_b64 s[0:1], exec
	v_readlane_b32 s4, v249, 5
	v_readlane_b32 s5, v249, 6
	s_and_b64 s[4:5], s[0:1], s[4:5]
	s_mov_b64 exec, s[4:5]
	s_cbranch_execz .LBB0_751
	v_readlane_b32 s3, v255, 7
	s_waitcnt vmcnt(0) expcnt(0) lgkmcnt(0)
	s_nop 0
	v_mov_b32_e32 v2, s3
	ds_read_b32 v4, v2
	v_readlane_b32 s3, v255, 8
	s_waitcnt lgkmcnt(0)
	v_cmp_ne_u32_e32 vcc, 0, v4
	v_mov_b32_e32 v2, s3
	ds_read_b32 v2, v2
	s_cbranch_vccnz .LBB0_715
	v_readlane_b32 s6, v249, 0
	v_readlane_b32 s7, v249, 1
	s_load_dwordx2 s[4:5], s[6:7], 0x4
	s_mov_b32 s14, 1
	s_waitcnt lgkmcnt(0)
	s_mul_i32 s3, s4, s85
	s_mul_i32 s3, s3, s5
	s_branch .LBB0_703

; __device__ __forceinline__ void sconv_item(const Args& args, int l, int item, int lane) {
;     asm volatile("" : "+v"(lane));
;     unsigned char* ws = args.ws;
;     const bf16_t* PROJ = (const bf16_t*)(ws + WS_PROJ); bf16_t* ACONV = (bf16_t*)(ws + WS_ABR + SZ_ABR1);
;     const int tb = item >> 1, c0 = (item & 1) * 512 + lane * 8, row0 = tb * 8;
; __global__ void __launch_bounds__(512, 2) mk_fwd(Args args) {
;     ...
;                 if (vcu >= 64) for (int it = (vcu - 64) * 8 + wave; it < (MT / 8) * 2; it += 192 * 8) sconv_item(args, l, it, lane);
.LBB0_685:
	v_readlane_b32 s98, v255, 44
	v_readlane_b32 s99, v255, 45
	s_nop 1
	s_add_i32 s14, s14, s98
	s_lshl_b32 s24, s98, 9
	s_add_i32 s3, s3, s24
	s_lshl_b32 s24, s98, 2
	s_add_i32 s2, s2, s24
	s_cmp_gt_i32 s14, s99
	s_mov_b32 s24, 0x10000
	s_cbranch_scc1 .LBB0_659
